# in-proj tail-round loop: unused B half-tiles no longer staged (4 fewer LDS-DMA + their scalar setup per two K-tiles per wave), waits retuned (on top of gsaddr2)
# speedup vs baseline: 1.0040x; 1.0040x over previous
; #define PG8_STAGE(bufoff, gbase, voff) do { _Pragma("unroll") for (int _i = 0; _i < 2; ++_i) \
;         __builtin_amdgcn_global_load_lds((const unsigned*)((const char*)(gbase) + (voff)[_i]), (PG8_LAS unsigned*)(lds + (bufoff) + ldsw + _i * 8192), 16, 0, 0); } while (0)
; #define PG8_LDA(dst, b, h) do { _Pragma("unroll") for (int m = 0; m < 4; ++m) _Pragma("unroll") for (int k = 0; k < 2; ++k) dst[m][k] = *(const PG8_LAS bf16x8*)(lds + PG8_SA(b, h) + aoff + m * 2048 + k * 1024); } while (0)
; #define PG8_LDB(dst, b, h) do { _Pragma("unroll") for (int n = 0; n < 2; ++n) _Pragma("unroll") for (int k = 0; k < 2; ++k) dst[n][k] = *(const PG8_LAS bf16x8*)(lds + PG8_SB(b, h) + boff + n * 2048 + k * 1024); } while (0)
; #define PG8_MMA(ai, bj, At, Bt) do { __builtin_amdgcn_s_setprio(1); _Pragma("unroll") for (int m = 0; m < 4; ++m) _Pragma("unroll") for (int n = 0; n < 2; ++n) _Pragma("unroll") for (int k = 0; k < 2; ++k) \
;         acc[ai][bj][m][n] = __builtin_amdgcn_mfma_f32_16x16x32_bf16(Bt[n][k], At[m][k], acc[ai][bj][m][n], 0, 0, 0); __builtin_amdgcn_s_setprio(0); } while (0)
; #define PG8_WAIT_V(n) asm volatile("s_waitcnt vmcnt(" #n ")" ::: "memory")
; #define PG8_WAIT_L(n) asm volatile("s_waitcnt lgkmcnt(" #n ")" ::: "memory")
; #define PG8_BAR __builtin_amdgcn_s_barrier()
; #define PG8_SCHED __builtin_amdgcn_sched_barrier(0)
; template <class Epi, class Sched, bool ALIGN_EPI = false, bool SP2 = false>
; __device__ __forceinline__ void gemm_phase(PG8_LAS unsigned char* lds, const Gemm g, const Sched& S, const Epi& E) {
;     ...
;             PG8_LDB(B0, 0, 0); PG8_LDB(B1, 0, 1); PG8_SCHED; PG8_LDA(At, 0, 0); PG8_STAGE(PG8_SA(1, 1), a1 + hstep, voffA);
;             PG8_WAIT_V(8); PG8_WAIT_L(0); PG8_BAR; PG8_MMA(0, 0, At, B0); PG8_MMA(0, 1, At, B1); PG8_BAR; PG8_SCHED;
;             PG8_LDA(At, 0, 1); PG8_STAGE(PG8_SB(0, 0), b2, voffB); PG8_STAGE(PG8_SB(0, 1), b2 + hstep, voffB); PG8_STAGE(PG8_SA(0, 0), a2, voffA);
;             PG8_WAIT_V(8); PG8_WAIT_L(0); PG8_BAR; PG8_MMA(1, 0, At, B0); PG8_MMA(1, 1, At, B1); PG8_BAR; PG8_SCHED;
.Ltail_loop:
	ds_read_b128 v[114:117], v242
	ds_read_b128 v[118:121], v242 offset:1024
	ds_read_b128 v[130:133], v242 offset:2048
	ds_read_b128 v[134:137], v242 offset:3072
	s_add_u32 s40, s34, 0xfff80080
	s_addc_u32 s41, s35, -1
	s_cmp_eq_u32 s46, 28
	s_cselect_b32 s43, s15, s41
	s_cselect_b32 s42, s19, s40
	s_cselect_b32 s41, s17, s45
	s_cselect_b32 s40, s37, s44
	s_add_i32 m0, s8, 0xc000
	ds_read_b128 v[180:183], v178
	ds_read_b128 v[184:187], v178 offset:1024
	ds_read_b128 v[188:191], v178 offset:2048
	ds_read_b128 v[192:195], v178 offset:3072
	ds_read_b128 v[196:199], v178 offset:4096
	ds_read_b128 v[200:203], v178 offset:5120
	ds_read_b128 v[208:211], v178 offset:6144
	ds_read_b128 v[230:233], v178 offset:7168
	global_load_lds_dwordx4 v164, s[34:35]
	s_add_i32 m0, s8, 0xe000
	s_nop 0
	global_load_lds_dwordx4 v166, s[34:35]
	s_waitcnt vmcnt(6)
	s_waitcnt lgkmcnt(0)
	s_barrier
	s_setprio 1
	v_mfma_f32_16x16x32_bf16 v[142:145], v[114:117], v[180:183], v[142:145]
	v_mfma_f32_16x16x32_bf16 v[138:141], v[130:133], v[180:183], v[138:141]
	v_mfma_f32_16x16x32_bf16 v[110:113], v[114:117], v[188:191], v[110:113]
	v_mfma_f32_16x16x32_bf16 v[106:109], v[130:133], v[188:191], v[106:109]
	v_mfma_f32_16x16x32_bf16 v[94:97], v[114:117], v[196:199], v[94:97]
	v_mfma_f32_16x16x32_bf16 v[90:93], v[130:133], v[196:199], v[90:93]
	v_mfma_f32_16x16x32_bf16 v[78:81], v[114:117], v[208:211], v[78:81]
	v_mfma_f32_16x16x32_bf16 v[74:77], v[130:133], v[208:211], v[74:77]
	v_mfma_f32_16x16x32_bf16 v[142:145], v[118:121], v[184:187], v[142:145]
	v_mfma_f32_16x16x32_bf16 v[138:141], v[134:137], v[184:187], v[138:141]
	v_mfma_f32_16x16x32_bf16 v[110:113], v[118:121], v[192:195], v[110:113]
	v_mfma_f32_16x16x32_bf16 v[106:109], v[134:137], v[192:195], v[106:109]
	v_mfma_f32_16x16x32_bf16 v[94:97], v[118:121], v[200:203], v[94:97]
	v_mfma_f32_16x16x32_bf16 v[90:93], v[134:137], v[200:203], v[90:93]
	v_mfma_f32_16x16x32_bf16 v[78:81], v[118:121], v[230:233], v[78:81]
	v_mfma_f32_16x16x32_bf16 v[74:77], v[134:137], v[230:233], v[74:77]
	s_setprio 0
	s_barrier
	s_add_i32 s47, s88, s6
	s_mov_b32 m0, s47
	ds_read_b128 v[180:183], v178 offset:16384
	ds_read_b128 v[184:187], v178 offset:17408
	ds_read_b128 v[188:191], v178 offset:18432
	ds_read_b128 v[192:195], v178 offset:19456
	ds_read_b128 v[196:199], v178 offset:20480
	ds_read_b128 v[200:203], v178 offset:21504
	ds_read_b128 v[208:211], v178 offset:22528
	ds_read_b128 v[230:233], v178 offset:23552
	global_load_lds_dwordx4 v0, s[40:41]
	s_add_i32 m0, s47, 0x2000
	s_nop 0
	global_load_lds_dwordx4 v154, s[40:41]
	s_mov_b32 m0, s8
	s_nop 0
	global_load_lds_dwordx4 v158, s[42:43]
	s_mov_b32 m0, s9
	s_nop 0
	global_load_lds_dwordx4 v156, s[42:43]
	s_waitcnt vmcnt(6)
	s_waitcnt lgkmcnt(0)
	s_barrier
	s_setprio 1
	v_mfma_f32_16x16x32_bf16 v[62:65], v[114:117], v[180:183], v[62:65]
	v_mfma_f32_16x16x32_bf16 v[58:61], v[130:133], v[180:183], v[58:61]
	v_mfma_f32_16x16x32_bf16 v[46:49], v[114:117], v[188:191], v[46:49]
	v_mfma_f32_16x16x32_bf16 v[42:45], v[130:133], v[188:191], v[42:45]
	v_mfma_f32_16x16x32_bf16 v[30:33], v[114:117], v[196:199], v[30:33]
	v_mfma_f32_16x16x32_bf16 v[26:29], v[130:133], v[196:199], v[26:29]
	v_mfma_f32_16x16x32_bf16 v[14:17], v[114:117], v[208:211], v[14:17]
	v_mfma_f32_16x16x32_bf16 v[10:13], v[130:133], v[208:211], v[10:13]
	v_mfma_f32_16x16x32_bf16 v[62:65], v[118:121], v[184:187], v[62:65]
	v_mfma_f32_16x16x32_bf16 v[58:61], v[134:137], v[184:187], v[58:61]
	v_mfma_f32_16x16x32_bf16 v[46:49], v[118:121], v[192:195], v[46:49]
	v_mfma_f32_16x16x32_bf16 v[42:45], v[134:137], v[192:195], v[42:45]
	v_mfma_f32_16x16x32_bf16 v[30:33], v[118:121], v[200:203], v[30:33]
	v_mfma_f32_16x16x32_bf16 v[26:29], v[134:137], v[200:203], v[26:29]
	v_mfma_f32_16x16x32_bf16 v[14:17], v[118:121], v[230:233], v[14:17]
	v_mfma_f32_16x16x32_bf16 v[10:13], v[134:137], v[230:233], v[10:13]
	s_setprio 0
	s_barrier
; #define PG8_STAGE(bufoff, gbase, voff) do { _Pragma("unroll") for (int _i = 0; _i < 2; ++_i) \
;         __builtin_amdgcn_global_load_lds((const unsigned*)((const char*)(gbase) + (voff)[_i]), (PG8_LAS unsigned*)(lds + (bufoff) + ldsw + _i * 8192), 16, 0, 0); } while (0)
; #define PG8_LDA(dst, b, h) do { _Pragma("unroll") for (int m = 0; m < 4; ++m) _Pragma("unroll") for (int k = 0; k < 2; ++k) dst[m][k] = *(const PG8_LAS bf16x8*)(lds + PG8_SA(b, h) + aoff + m * 2048 + k * 1024); } while (0)
; #define PG8_LDB(dst, b, h) do { _Pragma("unroll") for (int n = 0; n < 2; ++n) _Pragma("unroll") for (int k = 0; k < 2; ++k) dst[n][k] = *(const PG8_LAS bf16x8*)(lds + PG8_SB(b, h) + boff + n * 2048 + k * 1024); } while (0)
; #define PG8_MMA(ai, bj, At, Bt) do { __builtin_amdgcn_s_setprio(1); _Pragma("unroll") for (int m = 0; m < 4; ++m) _Pragma("unroll") for (int n = 0; n < 2; ++n) _Pragma("unroll") for (int k = 0; k < 2; ++k) \
;         acc[ai][bj][m][n] = __builtin_amdgcn_mfma_f32_16x16x32_bf16(Bt[n][k], At[m][k], acc[ai][bj][m][n], 0, 0, 0); __builtin_amdgcn_s_setprio(0); } while (0)
; #define PG8_WAIT_V(n) asm volatile("s_waitcnt vmcnt(" #n ")" ::: "memory")
; #define PG8_WAIT_L(n) asm volatile("s_waitcnt lgkmcnt(" #n ")" ::: "memory")
; #define PG8_BAR __builtin_amdgcn_s_barrier()
; #define PG8_SCHED __builtin_amdgcn_sched_barrier(0)
; template <class Epi, class Sched, bool ALIGN_EPI = false, bool SP2 = false>
; __device__ __forceinline__ void gemm_phase(PG8_LAS unsigned char* lds, const Gemm g, const Sched& S, const Epi& E) {
;     ...
;         for (int t = 0; t < nt; t += 2) {
;     ...
;             PG8_LDB(B0, 1, 0); PG8_LDB(B1, 1, 1); PG8_SCHED; PG8_LDA(At, 1, 0); PG8_STAGE(PG8_SA(0, 1), a2 + hstep, voffA);
;             PG8_WAIT_V(8); PG8_WAIT_L(0); PG8_BAR; PG8_MMA(0, 0, At, B0); PG8_MMA(0, 1, At, B1); PG8_BAR; PG8_SCHED;
;             PG8_LDA(At, 1, 1); PG8_STAGE(PG8_SB(1, 0), b3, voffB); PG8_STAGE(PG8_SB(1, 1), b3 + hstep, voffB); PG8_STAGE(PG8_SA(1, 0), a3, voffA);
;             PG8_WAIT_V(8); PG8_WAIT_L(0); PG8_BAR; PG8_MMA(1, 0, At, B0); PG8_MMA(1, 1, At, B1); PG8_BAR; PG8_SCHED;
	ds_read_b128 v[114:117], v244
	ds_read_b128 v[118:121], v244 offset:1024
	ds_read_b128 v[130:133], v244 offset:2048
	ds_read_b128 v[134:137], v244 offset:3072
	s_add_u32 s50, s42, 0x80000
	s_addc_u32 s51, s43, 0
	s_mov_b32 m0, s10
	ds_read_b128 v[180:183], v178 offset:32768
	ds_read_b128 v[184:187], v178 offset:33792
	ds_read_b128 v[188:191], v178 offset:34816
	ds_read_b128 v[192:195], v178 offset:35840
	ds_read_b128 v[196:199], v178 offset:36864
	ds_read_b128 v[200:203], v178 offset:37888
	ds_read_b128 v[208:211], v178 offset:38912
	ds_read_b128 v[230:233], v178 offset:39936
	global_load_lds_dwordx4 v158, s[50:51]
	s_mov_b32 m0, s11
	s_nop 0
	global_load_lds_dwordx4 v156, s[50:51]
	s_waitcnt vmcnt(6)
	s_waitcnt lgkmcnt(0)
	s_barrier
	s_setprio 1
	v_mfma_f32_16x16x32_bf16 v[142:145], v[114:117], v[180:183], v[142:145]
	v_mfma_f32_16x16x32_bf16 v[138:141], v[130:133], v[180:183], v[138:141]
	v_mfma_f32_16x16x32_bf16 v[110:113], v[114:117], v[188:191], v[110:113]
	v_mfma_f32_16x16x32_bf16 v[106:109], v[130:133], v[188:191], v[106:109]
	v_mfma_f32_16x16x32_bf16 v[94:97], v[114:117], v[196:199], v[94:97]
	v_mfma_f32_16x16x32_bf16 v[90:93], v[130:133], v[196:199], v[90:93]
	v_mfma_f32_16x16x32_bf16 v[78:81], v[114:117], v[208:211], v[78:81]
	v_mfma_f32_16x16x32_bf16 v[74:77], v[130:133], v[208:211], v[74:77]
	v_mfma_f32_16x16x32_bf16 v[142:145], v[118:121], v[184:187], v[142:145]
	v_mfma_f32_16x16x32_bf16 v[138:141], v[134:137], v[184:187], v[138:141]
	v_mfma_f32_16x16x32_bf16 v[110:113], v[118:121], v[192:195], v[110:113]
	v_mfma_f32_16x16x32_bf16 v[106:109], v[134:137], v[192:195], v[106:109]
	v_mfma_f32_16x16x32_bf16 v[94:97], v[118:121], v[200:203], v[94:97]
	v_mfma_f32_16x16x32_bf16 v[90:93], v[134:137], v[200:203], v[90:93]
	v_mfma_f32_16x16x32_bf16 v[78:81], v[118:121], v[230:233], v[78:81]
	v_mfma_f32_16x16x32_bf16 v[74:77], v[134:137], v[230:233], v[74:77]
	s_setprio 0
	s_barrier
	s_add_i32 vcc_lo, s90, s6
	s_add_u32 s50, s40, 0x80
	s_addc_u32 s51, s41, 0
	s_mov_b32 m0, vcc_lo
	ds_read_b128 v[180:183], v178 offset:49152
	ds_read_b128 v[184:187], v178 offset:50176
	ds_read_b128 v[188:191], v178 offset:51200
	ds_read_b128 v[192:195], v178 offset:52224
	ds_read_b128 v[196:199], v178 offset:53248
	ds_read_b128 v[200:203], v178 offset:54272
	ds_read_b128 v[208:211], v178 offset:55296
	ds_read_b128 v[230:233], v178 offset:56320
	global_load_lds_dwordx4 v0, s[50:51]
	s_add_i32 m0, vcc_lo, 0x2000
	s_nop 0
	global_load_lds_dwordx4 v154, s[50:51]
	s_add_u32 s50, s42, 0x80
	s_addc_u32 s51, s43, 0
	s_mov_b32 m0, s13
	s_nop 0
	global_load_lds_dwordx4 v158, s[50:51]
	s_mov_b32 m0, s25
	s_nop 0
	global_load_lds_dwordx4 v156, s[50:51]
	s_waitcnt vmcnt(6)
	s_waitcnt lgkmcnt(0)
	s_barrier
	s_setprio 1
	v_mfma_f32_16x16x32_bf16 v[62:65], v[114:117], v[180:183], v[62:65]
	v_mfma_f32_16x16x32_bf16 v[58:61], v[130:133], v[180:183], v[58:61]
	v_mfma_f32_16x16x32_bf16 v[46:49], v[114:117], v[188:191], v[46:49]
	v_mfma_f32_16x16x32_bf16 v[42:45], v[130:133], v[188:191], v[42:45]
	v_mfma_f32_16x16x32_bf16 v[30:33], v[114:117], v[196:199], v[30:33]
	v_mfma_f32_16x16x32_bf16 v[26:29], v[130:133], v[196:199], v[26:29]
	v_mfma_f32_16x16x32_bf16 v[14:17], v[114:117], v[208:211], v[14:17]
	v_mfma_f32_16x16x32_bf16 v[10:13], v[130:133], v[208:211], v[10:13]
	v_mfma_f32_16x16x32_bf16 v[62:65], v[118:121], v[184:187], v[62:65]
	v_mfma_f32_16x16x32_bf16 v[58:61], v[134:137], v[184:187], v[58:61]
	v_mfma_f32_16x16x32_bf16 v[46:49], v[118:121], v[192:195], v[46:49]
	v_mfma_f32_16x16x32_bf16 v[42:45], v[134:137], v[192:195], v[42:45]
	v_mfma_f32_16x16x32_bf16 v[30:33], v[118:121], v[200:203], v[30:33]
	v_mfma_f32_16x16x32_bf16 v[26:29], v[134:137], v[200:203], v[26:29]
	v_mfma_f32_16x16x32_bf16 v[14:17], v[118:121], v[230:233], v[14:17]
	v_mfma_f32_16x16x32_bf16 v[10:13], v[134:137], v[230:233], v[10:13]
	s_setprio 0
	s_add_i32 s46, s46, 2
	s_add_u32 s34, s34, 0x100
	s_addc_u32 s35, s35, 0
	s_add_u32 s44, s44, 0x100
	s_addc_u32 s45, s45, 0
	s_cmp_gt_u32 s46, 29
	s_barrier
	s_cbranch_scc0 .Ltail_loop
	s_branch .Ltail_join
